# v077 stack + DPP row sums also in the input-conversion and final-RMSNorm row passes
# speedup vs baseline: 1.0080x; 1.0041x over previous
.LBB0_249:
	s_min_i32 s7, s6, 0x8000
	s_ashr_i32 s7, s7, 11
	s_mul_hi_i32 s9, s7, 0x6000
	s_mulk_i32 s7, 0x6000
	s_add_u32 s7, s44, s7
	s_addc_u32 s9, s45, s9
	s_add_u32 s12, s7, 0x1000
	s_addc_u32 s13, s9, 0
	v_lshl_add_u64 v[66:67], v[116:117], 2, s[12:13]
	global_load_dwordx4 v[128:131], v[66:67], off
	s_ashr_i32 s7, s6, 31
	s_lshl_b64 s[14:15], s[6:7], 11
	v_lshl_add_u64 v[132:133], v[126:127], 0, s[14:15]
	v_lshl_add_u64 v[66:67], v[118:119], 2, s[12:13]
	s_waitcnt vmcnt(4)
	v_mul_f32_e32 v64, v17, v17
	s_waitcnt vmcnt(3)
	v_mul_f32_e32 v134, v23, v23
	s_waitcnt vmcnt(2)
	v_mul_f32_e32 v135, v25, v25
	v_mul_f32_e32 v136, v27, v27
	v_fmac_f32_e32 v64, v16, v16
	v_fmac_f32_e32 v134, v22, v22
	s_waitcnt vmcnt(1)
	v_mul_f32_e32 v137, v29, v29
	v_mul_f32_e32 v138, v31, v31
	v_fmac_f32_e32 v135, v24, v24
	v_fmac_f32_e32 v136, v26, v26
	v_fmac_f32_e32 v137, v28, v28
	v_fmac_f32_e32 v138, v30, v30
	s_waitcnt vmcnt(0)
	v_pk_add_f32 v[128:129], v[128:129], 1.0 op_sel_hi:[1,0]
	v_pk_add_f32 v[130:131], v[130:131], 1.0 op_sel_hi:[1,0]
	v_pk_mul_f32 v[128:129], v[0:1], v[128:129]
	v_pk_mul_f32 v[130:131], v[2:3], v[130:131]
	v_pk_mul_f32 v[128:129], v[16:17], v[128:129]
	v_pk_mul_f32 v[130:131], v[18:19], v[130:131]
	v_cvt_pk_bf16_f32 v128, v128, v129
	s_nop 0
	v_cvt_pk_bf16_f32 v129, v130, v131
	global_store_dwordx2 v[132:133], v[128:129], off
	global_load_dwordx4 v[128:131], v[66:67], off
	v_lshl_add_u64 v[66:67], v[120:121], 2, s[12:13]
	s_waitcnt vmcnt(0)
	v_pk_add_f32 v[128:129], v[128:129], 1.0 op_sel_hi:[1,0]
	v_pk_add_f32 v[130:131], v[130:131], 1.0 op_sel_hi:[1,0]
	v_pk_mul_f32 v[128:129], v[4:5], v[128:129]
	v_pk_mul_f32 v[130:131], v[6:7], v[130:131]
	v_pk_mul_f32 v[128:129], v[20:21], v[128:129]
	v_pk_mul_f32 v[130:131], v[22:23], v[130:131]
	v_cvt_pk_bf16_f32 v128, v128, v129
	s_nop 0
	v_cvt_pk_bf16_f32 v129, v130, v131
	global_store_dwordx2 v[132:133], v[128:129], off offset:512
	global_load_dwordx4 v[128:131], v[66:67], off
	v_lshl_add_u64 v[66:67], v[122:123], 2, s[12:13]
	s_waitcnt vmcnt(0)
	v_pk_add_f32 v[128:129], v[128:129], 1.0 op_sel_hi:[1,0]
	v_pk_add_f32 v[130:131], v[130:131], 1.0 op_sel_hi:[1,0]
	v_pk_mul_f32 v[128:129], v[8:9], v[128:129]
	v_pk_mul_f32 v[130:131], v[10:11], v[130:131]
	v_pk_mul_f32 v[128:129], v[24:25], v[128:129]
	v_pk_mul_f32 v[130:131], v[26:27], v[130:131]
	v_cvt_pk_bf16_f32 v128, v128, v129
	s_nop 0
	v_cvt_pk_bf16_f32 v129, v130, v131
	global_store_dwordx2 v[132:133], v[128:129], off offset:1024
	global_load_dwordx4 v[128:131], v[66:67], off
	v_mul_f32_e32 v66, v19, v19
	v_mul_f32_e32 v67, v21, v21
	v_fmac_f32_e32 v66, v18, v18
	v_fmac_f32_e32 v67, v20, v20
	v_add_f32_e32 v64, v64, v66
	v_add_f32_e32 v66, v67, v134
	v_add_f32_e32 v67, v135, v136
	v_add_f32_e32 v64, v64, v66
	v_add_f32_e32 v134, v137, v138
	v_add_f32_e32 v64, v64, v67
	v_add_f32_e32 v64, v64, v134
	s_nop 1
	v_add_f32_dpp v64, v64, v64 quad_perm:[1,0,3,2] row_mask:0xf bank_mask:0xf
	s_nop 1
	v_add_f32_dpp v64, v64, v64 quad_perm:[2,3,0,1] row_mask:0xf bank_mask:0xf
	s_nop 1
	v_add_f32_dpp v64, v64, v64 row_half_mirror row_mask:0xf bank_mask:0xf
	s_nop 1
	v_add_f32_dpp v64, v64, v64 row_mirror row_mask:0xf bank_mask:0xf
	ds_swizzle_b32 v66, v64 offset:swizzle(SWAP,16)
	s_waitcnt lgkmcnt(0)
	v_add_f32_e32 v64, v64, v66
	v_mov_b32_e32 v66, v64
	s_nop 1
	v_permlane32_swap_b32_e32 v64, v66
	s_waitcnt vmcnt(0)
	v_pk_add_f32 v[128:129], v[128:129], 1.0 op_sel_hi:[1,0]
	v_pk_add_f32 v[130:131], v[130:131], 1.0 op_sel_hi:[1,0]
	v_pk_mul_f32 v[128:129], v[12:13], v[128:129]
	v_pk_mul_f32 v[130:131], v[14:15], v[130:131]
	v_pk_mul_f32 v[128:129], v[28:29], v[128:129]
	v_pk_mul_f32 v[130:131], v[30:31], v[130:131]
	v_cvt_pk_bf16_f32 v128, v128, v129
	s_nop 0
	v_cvt_pk_bf16_f32 v129, v130, v131
	global_store_dwordx2 v[132:133], v[128:129], off offset:1536
	s_and_saveexec_b64 s[12:13], s[2:3]
	s_cbranch_execz .LBB0_255
	v_add_f32_e32 v64, v64, v66
	s_lshl_b64 s[14:15], s[6:7], 6
	v_cndmask_b32_e64 v64, 0, v64, s[4:5]
	v_lshl_add_u64 v[128:129], v[124:125], 0, s[14:15]
	v_mov_b32_e32 v66, v65
	v_mov_b32_e32 v67, v65
	global_store_dwordx4 v[128:129], v[64:67], off
	s_or_b64 exec, exec, s[12:13]
	s_add_i32 s12, s26, s6
	s_cmp_gt_i32 s12, 0x8fff
	s_cbranch_scc0 .LBB0_256

.LBB0_252:
	s_min_i32 s7, s12, 0x8000
	s_ashr_i32 s7, s7, 11
	s_mul_hi_i32 s9, s7, 0x6000
	s_mulk_i32 s7, 0x6000
	s_add_u32 s7, s44, s7
	s_addc_u32 s9, s45, s9
	s_add_u32 s14, s7, 0x1000
	s_addc_u32 s15, s9, 0
	v_lshl_add_u64 v[66:67], v[116:117], 2, s[14:15]
	global_load_dwordx4 v[128:131], v[66:67], off
	s_ashr_i32 s13, s12, 31
	s_lshl_b64 s[20:21], s[12:13], 11
	v_lshl_add_u64 v[132:133], v[126:127], 0, s[20:21]
	v_lshl_add_u64 v[66:67], v[118:119], 2, s[14:15]
	v_mul_f32_e32 v64, v49, v49
	v_mul_f32_e32 v134, v55, v55
	v_mul_f32_e32 v135, v57, v57
	v_mul_f32_e32 v136, v59, v59
	v_fmac_f32_e32 v64, v48, v48
	v_fmac_f32_e32 v134, v54, v54
	v_mul_f32_e32 v137, v61, v61
	v_mul_f32_e32 v138, v63, v63
	v_fmac_f32_e32 v135, v56, v56
	v_fmac_f32_e32 v136, v58, v58
	v_fmac_f32_e32 v137, v60, v60
	v_fmac_f32_e32 v138, v62, v62
	s_waitcnt vmcnt(0)
	v_pk_add_f32 v[128:129], v[128:129], 1.0 op_sel_hi:[1,0]
	v_pk_add_f32 v[130:131], v[130:131], 1.0 op_sel_hi:[1,0]
	v_pk_mul_f32 v[128:129], v[0:1], v[128:129]
	v_pk_mul_f32 v[130:131], v[2:3], v[130:131]
	v_pk_mul_f32 v[128:129], v[48:49], v[128:129]
	v_pk_mul_f32 v[130:131], v[50:51], v[130:131]
	v_cvt_pk_bf16_f32 v128, v128, v129
	s_nop 0
	v_cvt_pk_bf16_f32 v129, v130, v131
	global_store_dwordx2 v[132:133], v[128:129], off
	global_load_dwordx4 v[128:131], v[66:67], off
	v_lshl_add_u64 v[66:67], v[120:121], 2, s[14:15]
	s_waitcnt vmcnt(0)
	v_pk_add_f32 v[128:129], v[128:129], 1.0 op_sel_hi:[1,0]
	v_pk_add_f32 v[130:131], v[130:131], 1.0 op_sel_hi:[1,0]
	v_pk_mul_f32 v[128:129], v[4:5], v[128:129]
	v_pk_mul_f32 v[130:131], v[6:7], v[130:131]
	v_pk_mul_f32 v[128:129], v[52:53], v[128:129]
	v_pk_mul_f32 v[130:131], v[54:55], v[130:131]
	v_cvt_pk_bf16_f32 v128, v128, v129
	s_nop 0
	v_cvt_pk_bf16_f32 v129, v130, v131
	global_store_dwordx2 v[132:133], v[128:129], off offset:512
	global_load_dwordx4 v[128:131], v[66:67], off
	v_lshl_add_u64 v[66:67], v[122:123], 2, s[14:15]
	s_waitcnt vmcnt(0)
	v_pk_add_f32 v[128:129], v[128:129], 1.0 op_sel_hi:[1,0]
	v_pk_add_f32 v[130:131], v[130:131], 1.0 op_sel_hi:[1,0]
	v_pk_mul_f32 v[128:129], v[8:9], v[128:129]
	v_pk_mul_f32 v[130:131], v[10:11], v[130:131]
	v_pk_mul_f32 v[128:129], v[56:57], v[128:129]
	v_pk_mul_f32 v[130:131], v[58:59], v[130:131]
	v_cvt_pk_bf16_f32 v128, v128, v129
	s_nop 0
	v_cvt_pk_bf16_f32 v129, v130, v131
	global_store_dwordx2 v[132:133], v[128:129], off offset:1024
	global_load_dwordx4 v[128:131], v[66:67], off
	v_mul_f32_e32 v66, v51, v51
	v_mul_f32_e32 v67, v53, v53
	v_fmac_f32_e32 v66, v50, v50
	v_fmac_f32_e32 v67, v52, v52
	v_add_f32_e32 v64, v64, v66
	v_add_f32_e32 v66, v67, v134
	v_add_f32_e32 v67, v135, v136
	v_add_f32_e32 v64, v64, v66
	v_add_f32_e32 v134, v137, v138
	v_add_f32_e32 v64, v64, v67
	v_add_f32_e32 v64, v64, v134
	s_nop 1
	v_add_f32_dpp v64, v64, v64 quad_perm:[1,0,3,2] row_mask:0xf bank_mask:0xf
	s_nop 1
	v_add_f32_dpp v64, v64, v64 quad_perm:[2,3,0,1] row_mask:0xf bank_mask:0xf
	s_nop 1
	v_add_f32_dpp v64, v64, v64 row_half_mirror row_mask:0xf bank_mask:0xf
	s_nop 1
	v_add_f32_dpp v64, v64, v64 row_mirror row_mask:0xf bank_mask:0xf
	ds_swizzle_b32 v66, v64 offset:swizzle(SWAP,16)
	s_waitcnt lgkmcnt(0)
	v_add_f32_e32 v64, v64, v66
	v_mov_b32_e32 v66, v64
	s_nop 1
	v_permlane32_swap_b32_e32 v64, v66
	s_waitcnt vmcnt(0)
	v_pk_add_f32 v[128:129], v[128:129], 1.0 op_sel_hi:[1,0]
	v_pk_add_f32 v[130:131], v[130:131], 1.0 op_sel_hi:[1,0]
	v_pk_mul_f32 v[128:129], v[12:13], v[128:129]
	v_pk_mul_f32 v[130:131], v[14:15], v[130:131]
	v_pk_mul_f32 v[128:129], v[60:61], v[128:129]
	v_pk_mul_f32 v[130:131], v[62:63], v[130:131]
	v_cvt_pk_bf16_f32 v128, v128, v129
	s_nop 0
	v_cvt_pk_bf16_f32 v129, v130, v131
	global_store_dwordx2 v[132:133], v[128:129], off offset:1536
	s_and_saveexec_b64 s[14:15], s[2:3]
	s_cbranch_execz .LBB0_254
	v_add_f32_e32 v64, v64, v66
	s_lshl_b64 s[12:13], s[12:13], 6
	v_cndmask_b32_e64 v64, 0, v64, s[4:5]
	v_lshl_add_u64 v[128:129], v[124:125], 0, s[12:13]
	v_mov_b32_e32 v66, v65
	v_mov_b32_e32 v67, v65
	global_store_dwordx4 v[128:129], v[64:67], off

.LBB0_256:
	s_min_i32 s7, s12, 0x8000
	s_ashr_i32 s7, s7, 11
	s_mul_hi_i32 s9, s7, 0x6000
	s_mulk_i32 s7, 0x6000
	s_add_u32 s7, s44, s7
	s_addc_u32 s9, s45, s9
	s_add_u32 s14, s7, 0x1000
	s_addc_u32 s15, s9, 0
	v_lshl_add_u64 v[66:67], v[116:117], 2, s[14:15]
	global_load_dwordx4 v[128:131], v[66:67], off
	s_ashr_i32 s13, s12, 31
	s_lshl_b64 s[20:21], s[12:13], 11
	v_lshl_add_u64 v[132:133], v[126:127], 0, s[20:21]
	v_lshl_add_u64 v[66:67], v[118:119], 2, s[14:15]
	v_mul_f32_e32 v64, v33, v33
	v_mul_f32_e32 v134, v39, v39
	v_mul_f32_e32 v135, v41, v41
	v_mul_f32_e32 v136, v43, v43
	v_fmac_f32_e32 v64, v32, v32
	v_fmac_f32_e32 v134, v38, v38
	v_mul_f32_e32 v137, v45, v45
	v_mul_f32_e32 v138, v47, v47
	v_fmac_f32_e32 v135, v40, v40
	v_fmac_f32_e32 v136, v42, v42
	v_fmac_f32_e32 v137, v44, v44
	v_fmac_f32_e32 v138, v46, v46
	s_waitcnt vmcnt(0)
	v_pk_add_f32 v[128:129], v[128:129], 1.0 op_sel_hi:[1,0]
	v_pk_add_f32 v[130:131], v[130:131], 1.0 op_sel_hi:[1,0]
	v_pk_mul_f32 v[128:129], v[0:1], v[128:129]
	v_pk_mul_f32 v[130:131], v[2:3], v[130:131]
	v_pk_mul_f32 v[128:129], v[32:33], v[128:129]
	v_pk_mul_f32 v[130:131], v[34:35], v[130:131]
	v_cvt_pk_bf16_f32 v128, v128, v129
	s_nop 0
	v_cvt_pk_bf16_f32 v129, v130, v131
	global_store_dwordx2 v[132:133], v[128:129], off
	global_load_dwordx4 v[128:131], v[66:67], off
	v_lshl_add_u64 v[66:67], v[120:121], 2, s[14:15]
	s_waitcnt vmcnt(0)
	v_pk_add_f32 v[128:129], v[128:129], 1.0 op_sel_hi:[1,0]
	v_pk_add_f32 v[130:131], v[130:131], 1.0 op_sel_hi:[1,0]
	v_pk_mul_f32 v[128:129], v[4:5], v[128:129]
	v_pk_mul_f32 v[130:131], v[6:7], v[130:131]
	v_pk_mul_f32 v[128:129], v[36:37], v[128:129]
	v_pk_mul_f32 v[130:131], v[38:39], v[130:131]
	v_cvt_pk_bf16_f32 v128, v128, v129
	s_nop 0
	v_cvt_pk_bf16_f32 v129, v130, v131
	global_store_dwordx2 v[132:133], v[128:129], off offset:512
	global_load_dwordx4 v[128:131], v[66:67], off
	v_lshl_add_u64 v[66:67], v[122:123], 2, s[14:15]
	s_waitcnt vmcnt(0)
	v_pk_add_f32 v[128:129], v[128:129], 1.0 op_sel_hi:[1,0]
	v_pk_add_f32 v[130:131], v[130:131], 1.0 op_sel_hi:[1,0]
	v_pk_mul_f32 v[128:129], v[8:9], v[128:129]
	v_pk_mul_f32 v[130:131], v[10:11], v[130:131]
	v_pk_mul_f32 v[128:129], v[40:41], v[128:129]
	v_pk_mul_f32 v[130:131], v[42:43], v[130:131]
	v_cvt_pk_bf16_f32 v128, v128, v129
	s_nop 0
	v_cvt_pk_bf16_f32 v129, v130, v131
	global_store_dwordx2 v[132:133], v[128:129], off offset:1024
	global_load_dwordx4 v[128:131], v[66:67], off
	v_mul_f32_e32 v66, v35, v35
	v_mul_f32_e32 v67, v37, v37
	v_fmac_f32_e32 v66, v34, v34
	v_fmac_f32_e32 v67, v36, v36
	v_add_f32_e32 v64, v64, v66
	v_add_f32_e32 v66, v67, v134
	v_add_f32_e32 v67, v135, v136
	v_add_f32_e32 v64, v64, v66
	v_add_f32_e32 v134, v137, v138
	v_add_f32_e32 v64, v64, v67
	v_add_f32_e32 v64, v64, v134
	s_nop 1
	v_add_f32_dpp v64, v64, v64 quad_perm:[1,0,3,2] row_mask:0xf bank_mask:0xf
	s_nop 1
	v_add_f32_dpp v64, v64, v64 quad_perm:[2,3,0,1] row_mask:0xf bank_mask:0xf
	s_nop 1
	v_add_f32_dpp v64, v64, v64 row_half_mirror row_mask:0xf bank_mask:0xf
	s_nop 1
	v_add_f32_dpp v64, v64, v64 row_mirror row_mask:0xf bank_mask:0xf
	ds_swizzle_b32 v66, v64 offset:swizzle(SWAP,16)
	s_waitcnt lgkmcnt(0)
	v_add_f32_e32 v64, v64, v66
	v_mov_b32_e32 v66, v64
	s_nop 1
	v_permlane32_swap_b32_e32 v64, v66
	s_waitcnt vmcnt(0)
	v_pk_add_f32 v[128:129], v[128:129], 1.0 op_sel_hi:[1,0]
	v_pk_add_f32 v[130:131], v[130:131], 1.0 op_sel_hi:[1,0]
	v_pk_mul_f32 v[128:129], v[12:13], v[128:129]
	v_pk_mul_f32 v[130:131], v[14:15], v[130:131]
	v_pk_mul_f32 v[128:129], v[44:45], v[128:129]
	v_pk_mul_f32 v[130:131], v[46:47], v[130:131]
	v_cvt_pk_bf16_f32 v128, v128, v129
	s_nop 0
	v_cvt_pk_bf16_f32 v129, v130, v131
	global_store_dwordx2 v[132:133], v[128:129], off offset:1536
	s_and_saveexec_b64 s[14:15], s[2:3]
	s_cbranch_execz .LBB0_258
	v_add_f32_e32 v64, v64, v66
	s_lshl_b64 s[12:13], s[12:13], 6
	v_cndmask_b32_e64 v64, 0, v64, s[4:5]
	v_lshl_add_u64 v[128:129], v[124:125], 0, s[12:13]
	v_mov_b32_e32 v66, v65
	v_mov_b32_e32 v67, v65
	global_store_dwordx4 v[128:129], v[64:67], off

.LBB0_265:
	s_min_i32 s7, s8, 0x8000
	s_ashr_i32 s7, s7, 11
	s_mul_hi_i32 s9, s7, 0x6000
	s_mulk_i32 s7, 0x6000
	s_add_u32 s7, s44, s7
	s_addc_u32 s9, s45, s9
	s_add_u32 s10, s7, 0x1000
	s_addc_u32 s11, s9, 0
	v_lshl_add_u64 v[66:67], v[116:117], 2, s[10:11]
	global_load_dwordx4 v[128:131], v[66:67], off
	s_ashr_i32 s9, s8, 31
	s_lshl_b64 s[14:15], s[8:9], 11
	v_lshl_add_u64 v[132:133], v[126:127], 0, s[14:15]
	v_lshl_add_u64 v[66:67], v[118:119], 2, s[10:11]
	v_mul_f32_e32 v64, v101, v101
	v_mul_f32_e32 v134, v107, v107
	v_mul_f32_e32 v135, v109, v109
	v_mul_f32_e32 v136, v111, v111
	v_fmac_f32_e32 v64, v100, v100
	v_fmac_f32_e32 v134, v106, v106
	v_mul_f32_e32 v137, v113, v113
	v_mul_f32_e32 v138, v115, v115
	v_fmac_f32_e32 v135, v108, v108
	v_fmac_f32_e32 v136, v110, v110
	v_fmac_f32_e32 v137, v112, v112
	v_fmac_f32_e32 v138, v114, v114
	s_waitcnt vmcnt(0)
	v_pk_add_f32 v[128:129], v[128:129], 1.0 op_sel_hi:[1,0]
	v_pk_add_f32 v[130:131], v[130:131], 1.0 op_sel_hi:[1,0]
	v_pk_mul_f32 v[128:129], v[0:1], v[128:129]
	v_pk_mul_f32 v[130:131], v[2:3], v[130:131]
	v_pk_mul_f32 v[128:129], v[100:101], v[128:129]
	v_pk_mul_f32 v[130:131], v[102:103], v[130:131]
	v_cvt_pk_bf16_f32 v128, v128, v129
	s_nop 0
	v_cvt_pk_bf16_f32 v129, v130, v131
	global_store_dwordx2 v[132:133], v[128:129], off
	global_load_dwordx4 v[128:131], v[66:67], off
	v_lshl_add_u64 v[66:67], v[120:121], 2, s[10:11]
	s_waitcnt vmcnt(0)
	v_pk_add_f32 v[128:129], v[128:129], 1.0 op_sel_hi:[1,0]
	v_pk_add_f32 v[130:131], v[130:131], 1.0 op_sel_hi:[1,0]
	v_pk_mul_f32 v[128:129], v[4:5], v[128:129]
	v_pk_mul_f32 v[130:131], v[6:7], v[130:131]
	v_pk_mul_f32 v[128:129], v[104:105], v[128:129]
	v_pk_mul_f32 v[130:131], v[106:107], v[130:131]
	v_cvt_pk_bf16_f32 v128, v128, v129
	s_nop 0
	v_cvt_pk_bf16_f32 v129, v130, v131
	global_store_dwordx2 v[132:133], v[128:129], off offset:512
	global_load_dwordx4 v[128:131], v[66:67], off
	v_lshl_add_u64 v[66:67], v[122:123], 2, s[10:11]
	s_waitcnt vmcnt(0)
	v_pk_add_f32 v[128:129], v[128:129], 1.0 op_sel_hi:[1,0]
	v_pk_add_f32 v[130:131], v[130:131], 1.0 op_sel_hi:[1,0]
	v_pk_mul_f32 v[128:129], v[8:9], v[128:129]
	v_pk_mul_f32 v[130:131], v[10:11], v[130:131]
	v_pk_mul_f32 v[128:129], v[108:109], v[128:129]
	v_pk_mul_f32 v[130:131], v[110:111], v[130:131]
	v_cvt_pk_bf16_f32 v128, v128, v129
	s_nop 0
	v_cvt_pk_bf16_f32 v129, v130, v131
	global_store_dwordx2 v[132:133], v[128:129], off offset:1024
	global_load_dwordx4 v[128:131], v[66:67], off
	v_mul_f32_e32 v66, v103, v103
	v_mul_f32_e32 v67, v105, v105
	v_fmac_f32_e32 v66, v102, v102
	v_fmac_f32_e32 v67, v104, v104
	v_add_f32_e32 v64, v64, v66
	v_add_f32_e32 v66, v67, v134
	v_add_f32_e32 v67, v135, v136
	v_add_f32_e32 v64, v64, v66
	v_add_f32_e32 v134, v137, v138
	v_add_f32_e32 v64, v64, v67
	v_add_f32_e32 v64, v64, v134
	s_nop 1
	v_add_f32_dpp v64, v64, v64 quad_perm:[1,0,3,2] row_mask:0xf bank_mask:0xf
	s_nop 1
	v_add_f32_dpp v64, v64, v64 quad_perm:[2,3,0,1] row_mask:0xf bank_mask:0xf
	s_nop 1
	v_add_f32_dpp v64, v64, v64 row_half_mirror row_mask:0xf bank_mask:0xf
	s_nop 1
	v_add_f32_dpp v64, v64, v64 row_mirror row_mask:0xf bank_mask:0xf
	ds_swizzle_b32 v66, v64 offset:swizzle(SWAP,16)
	s_waitcnt lgkmcnt(0)
	v_add_f32_e32 v64, v64, v66
	v_mov_b32_e32 v66, v64
	s_nop 1
	v_permlane32_swap_b32_e32 v64, v66
	s_waitcnt vmcnt(0)
	v_pk_add_f32 v[128:129], v[128:129], 1.0 op_sel_hi:[1,0]
	v_pk_add_f32 v[130:131], v[130:131], 1.0 op_sel_hi:[1,0]
	v_pk_mul_f32 v[128:129], v[12:13], v[128:129]
	v_pk_mul_f32 v[130:131], v[14:15], v[130:131]
	v_pk_mul_f32 v[128:129], v[112:113], v[128:129]
	v_pk_mul_f32 v[130:131], v[114:115], v[130:131]
	v_cvt_pk_bf16_f32 v128, v128, v129
	s_nop 0
	v_cvt_pk_bf16_f32 v129, v130, v131
	global_store_dwordx2 v[132:133], v[128:129], off offset:1536
	s_and_saveexec_b64 s[10:11], s[2:3]
	s_cbranch_execz .LBB0_268
	v_add_f32_e32 v64, v64, v66
	s_lshl_b64 s[8:9], s[8:9], 6
	v_cndmask_b32_e64 v64, 0, v64, s[4:5]
	v_lshl_add_u64 v[128:129], v[124:125], 0, s[8:9]
	v_mov_b32_e32 v66, v65
	v_mov_b32_e32 v67, v65
	global_store_dwordx4 v[128:129], v[64:67], off
	s_or_b64 exec, exec, s[10:11]
	s_add_i32 s8, s0, s6
	s_cmp_gt_i32 s8, 0x8fff
	s_cbranch_scc0 .LBB0_269

.LBB0_269:
	s_min_i32 s7, s8, 0x8000
	s_ashr_i32 s7, s7, 11
	s_mul_hi_i32 s9, s7, 0x6000
	s_mulk_i32 s7, 0x6000
	s_add_u32 s7, s44, s7
	s_addc_u32 s9, s45, s9
	s_add_u32 s10, s7, 0x1000
	s_addc_u32 s11, s9, 0
	v_lshl_add_u64 v[66:67], v[116:117], 2, s[10:11]
	global_load_dwordx4 v[128:131], v[66:67], off
	s_ashr_i32 s9, s8, 31
	s_lshl_b64 s[14:15], s[8:9], 11
	v_lshl_add_u64 v[132:133], v[126:127], 0, s[14:15]
	v_lshl_add_u64 v[66:67], v[118:119], 2, s[10:11]
	v_mul_f32_e32 v64, v97, v97
	v_mul_f32_e32 v134, v95, v95
	v_mul_f32_e32 v135, v89, v89
	v_mul_f32_e32 v136, v91, v91
	v_fmac_f32_e32 v64, v96, v96
	v_fmac_f32_e32 v134, v94, v94
	v_mul_f32_e32 v137, v85, v85
	v_mul_f32_e32 v138, v87, v87
	v_fmac_f32_e32 v135, v88, v88
	v_fmac_f32_e32 v136, v90, v90
	v_fmac_f32_e32 v137, v84, v84
	v_fmac_f32_e32 v138, v86, v86
	s_waitcnt vmcnt(0)
	v_pk_add_f32 v[128:129], v[128:129], 1.0 op_sel_hi:[1,0]
	v_pk_add_f32 v[130:131], v[130:131], 1.0 op_sel_hi:[1,0]
	v_pk_mul_f32 v[128:129], v[0:1], v[128:129]
	v_pk_mul_f32 v[130:131], v[2:3], v[130:131]
	v_pk_mul_f32 v[128:129], v[96:97], v[128:129]
	v_pk_mul_f32 v[130:131], v[98:99], v[130:131]
	v_cvt_pk_bf16_f32 v128, v128, v129
	s_nop 0
	v_cvt_pk_bf16_f32 v129, v130, v131
	global_store_dwordx2 v[132:133], v[128:129], off
	global_load_dwordx4 v[128:131], v[66:67], off
	v_lshl_add_u64 v[66:67], v[120:121], 2, s[10:11]
	s_waitcnt vmcnt(0)
	v_pk_add_f32 v[128:129], v[128:129], 1.0 op_sel_hi:[1,0]
	v_pk_add_f32 v[130:131], v[130:131], 1.0 op_sel_hi:[1,0]
	v_pk_mul_f32 v[128:129], v[4:5], v[128:129]
	v_pk_mul_f32 v[130:131], v[6:7], v[130:131]
	v_pk_mul_f32 v[128:129], v[92:93], v[128:129]
	v_pk_mul_f32 v[130:131], v[94:95], v[130:131]
	v_cvt_pk_bf16_f32 v128, v128, v129
	s_nop 0
	v_cvt_pk_bf16_f32 v129, v130, v131
	global_store_dwordx2 v[132:133], v[128:129], off offset:512
	global_load_dwordx4 v[128:131], v[66:67], off
	v_lshl_add_u64 v[66:67], v[122:123], 2, s[10:11]
	s_waitcnt vmcnt(0)
	v_pk_add_f32 v[128:129], v[128:129], 1.0 op_sel_hi:[1,0]
	v_pk_add_f32 v[130:131], v[130:131], 1.0 op_sel_hi:[1,0]
	v_pk_mul_f32 v[128:129], v[8:9], v[128:129]
	v_pk_mul_f32 v[130:131], v[10:11], v[130:131]
	v_pk_mul_f32 v[128:129], v[88:89], v[128:129]
	v_pk_mul_f32 v[130:131], v[90:91], v[130:131]
	v_cvt_pk_bf16_f32 v128, v128, v129
	s_nop 0
	v_cvt_pk_bf16_f32 v129, v130, v131
	global_store_dwordx2 v[132:133], v[128:129], off offset:1024
	global_load_dwordx4 v[128:131], v[66:67], off
	v_mul_f32_e32 v66, v99, v99
	v_mul_f32_e32 v67, v93, v93
	v_fmac_f32_e32 v66, v98, v98
	v_fmac_f32_e32 v67, v92, v92
	v_add_f32_e32 v64, v64, v66
	v_add_f32_e32 v66, v67, v134
	v_add_f32_e32 v67, v135, v136
	v_add_f32_e32 v64, v64, v66
	v_add_f32_e32 v134, v137, v138
	v_add_f32_e32 v64, v64, v67
	v_add_f32_e32 v64, v64, v134
	s_nop 1
	v_add_f32_dpp v64, v64, v64 quad_perm:[1,0,3,2] row_mask:0xf bank_mask:0xf
	s_nop 1
	v_add_f32_dpp v64, v64, v64 quad_perm:[2,3,0,1] row_mask:0xf bank_mask:0xf
	s_nop 1
	v_add_f32_dpp v64, v64, v64 row_half_mirror row_mask:0xf bank_mask:0xf
	s_nop 1
	v_add_f32_dpp v64, v64, v64 row_mirror row_mask:0xf bank_mask:0xf
	ds_swizzle_b32 v66, v64 offset:swizzle(SWAP,16)
	s_waitcnt lgkmcnt(0)
	v_add_f32_e32 v64, v64, v66
	v_mov_b32_e32 v66, v64
	s_nop 1
	v_permlane32_swap_b32_e32 v64, v66
	s_waitcnt vmcnt(0)
	v_pk_add_f32 v[128:129], v[128:129], 1.0 op_sel_hi:[1,0]
	v_pk_add_f32 v[130:131], v[130:131], 1.0 op_sel_hi:[1,0]
	v_pk_mul_f32 v[128:129], v[12:13], v[128:129]
	v_pk_mul_f32 v[130:131], v[14:15], v[130:131]
	v_pk_mul_f32 v[128:129], v[84:85], v[128:129]
	v_pk_mul_f32 v[130:131], v[86:87], v[130:131]
	v_cvt_pk_bf16_f32 v128, v128, v129
	s_nop 0
	v_cvt_pk_bf16_f32 v129, v130, v131
	global_store_dwordx2 v[132:133], v[128:129], off offset:1536
	s_and_saveexec_b64 s[10:11], s[2:3]
	s_cbranch_execz .LBB0_271
	v_add_f32_e32 v64, v64, v66
	s_lshl_b64 s[8:9], s[8:9], 6
	v_cndmask_b32_e64 v64, 0, v64, s[4:5]
	v_lshl_add_u64 v[128:129], v[124:125], 0, s[8:9]
	v_mov_b32_e32 v66, v65
	v_mov_b32_e32 v67, v65
	global_store_dwordx4 v[128:129], v[64:67], off

.LBB0_272:
	s_min_i32 s7, s6, 0x8000
	s_ashr_i32 s7, s7, 11
	s_mul_hi_i32 s8, s7, 0x6000
	s_mulk_i32 s7, 0x6000
	s_add_u32 s7, s44, s7
	s_addc_u32 s9, s45, s8
	s_add_u32 s8, s7, 0x1000
	s_addc_u32 s9, s9, 0
	v_lshl_add_u64 v[66:67], v[116:117], 2, s[8:9]
	global_load_dwordx4 v[128:131], v[66:67], off
	s_ashr_i32 s7, s6, 31
	s_lshl_b64 s[10:11], s[6:7], 11
	v_lshl_add_u64 v[132:133], v[126:127], 0, s[10:11]
	v_lshl_add_u64 v[66:67], v[118:119], 2, s[8:9]
	v_mul_f32_e32 v64, v81, v81
	v_mul_f32_e32 v134, v79, v79
	v_mul_f32_e32 v135, v73, v73
	v_mul_f32_e32 v136, v75, v75
	v_fmac_f32_e32 v64, v80, v80
	v_fmac_f32_e32 v134, v78, v78
	v_mul_f32_e32 v137, v69, v69
	v_mul_f32_e32 v138, v71, v71
	v_fmac_f32_e32 v135, v72, v72
	v_fmac_f32_e32 v136, v74, v74
	v_fmac_f32_e32 v137, v68, v68
	v_fmac_f32_e32 v138, v70, v70
	s_waitcnt vmcnt(0)
	v_pk_add_f32 v[128:129], v[128:129], 1.0 op_sel_hi:[1,0]
	v_pk_add_f32 v[130:131], v[130:131], 1.0 op_sel_hi:[1,0]
	v_pk_mul_f32 v[128:129], v[0:1], v[128:129]
	v_pk_mul_f32 v[130:131], v[2:3], v[130:131]
	v_pk_mul_f32 v[128:129], v[80:81], v[128:129]
	v_pk_mul_f32 v[130:131], v[82:83], v[130:131]
	v_cvt_pk_bf16_f32 v128, v128, v129
	s_nop 0
	v_cvt_pk_bf16_f32 v129, v130, v131
	global_store_dwordx2 v[132:133], v[128:129], off
	global_load_dwordx4 v[128:131], v[66:67], off
	v_lshl_add_u64 v[66:67], v[120:121], 2, s[8:9]
	s_waitcnt vmcnt(0)
	v_pk_add_f32 v[128:129], v[128:129], 1.0 op_sel_hi:[1,0]
	v_pk_add_f32 v[130:131], v[130:131], 1.0 op_sel_hi:[1,0]
	v_pk_mul_f32 v[128:129], v[4:5], v[128:129]
	v_pk_mul_f32 v[130:131], v[6:7], v[130:131]
	v_pk_mul_f32 v[128:129], v[76:77], v[128:129]
	v_pk_mul_f32 v[130:131], v[78:79], v[130:131]
	v_cvt_pk_bf16_f32 v128, v128, v129
	s_nop 0
	v_cvt_pk_bf16_f32 v129, v130, v131
	global_store_dwordx2 v[132:133], v[128:129], off offset:512
	global_load_dwordx4 v[128:131], v[66:67], off
	v_lshl_add_u64 v[66:67], v[122:123], 2, s[8:9]
	s_waitcnt vmcnt(0)
	v_pk_add_f32 v[128:129], v[128:129], 1.0 op_sel_hi:[1,0]
	v_pk_add_f32 v[130:131], v[130:131], 1.0 op_sel_hi:[1,0]
	v_pk_mul_f32 v[128:129], v[8:9], v[128:129]
	v_pk_mul_f32 v[130:131], v[10:11], v[130:131]
	v_pk_mul_f32 v[128:129], v[72:73], v[128:129]
	v_pk_mul_f32 v[130:131], v[74:75], v[130:131]
	v_cvt_pk_bf16_f32 v128, v128, v129
	s_nop 0
	v_cvt_pk_bf16_f32 v129, v130, v131
	global_store_dwordx2 v[132:133], v[128:129], off offset:1024
	global_load_dwordx4 v[128:131], v[66:67], off
	v_mul_f32_e32 v66, v83, v83
	v_mul_f32_e32 v67, v77, v77
	v_fmac_f32_e32 v66, v82, v82
	v_fmac_f32_e32 v67, v76, v76
	v_add_f32_e32 v64, v64, v66
	v_add_f32_e32 v66, v67, v134
	v_add_f32_e32 v67, v135, v136
	v_add_f32_e32 v64, v64, v66
	v_add_f32_e32 v134, v137, v138
	v_add_f32_e32 v64, v64, v67
	v_add_f32_e32 v64, v64, v134
	s_nop 1
	v_add_f32_dpp v64, v64, v64 quad_perm:[1,0,3,2] row_mask:0xf bank_mask:0xf
	s_nop 1
	v_add_f32_dpp v64, v64, v64 quad_perm:[2,3,0,1] row_mask:0xf bank_mask:0xf
	s_nop 1
	v_add_f32_dpp v64, v64, v64 row_half_mirror row_mask:0xf bank_mask:0xf
	s_nop 1
	v_add_f32_dpp v64, v64, v64 row_mirror row_mask:0xf bank_mask:0xf
	ds_swizzle_b32 v66, v64 offset:swizzle(SWAP,16)
	s_waitcnt lgkmcnt(0)
	v_add_f32_e32 v64, v64, v66
	v_mov_b32_e32 v66, v64
	s_nop 1
	v_permlane32_swap_b32_e32 v64, v66
	s_waitcnt vmcnt(0)
	v_pk_add_f32 v[128:129], v[128:129], 1.0 op_sel_hi:[1,0]
	v_pk_add_f32 v[130:131], v[130:131], 1.0 op_sel_hi:[1,0]
	v_pk_mul_f32 v[128:129], v[12:13], v[128:129]
	v_pk_mul_f32 v[130:131], v[14:15], v[130:131]
	v_pk_mul_f32 v[128:129], v[68:69], v[128:129]
	v_pk_mul_f32 v[130:131], v[70:71], v[130:131]
	v_cvt_pk_bf16_f32 v128, v128, v129
	s_nop 0
	v_cvt_pk_bf16_f32 v129, v130, v131
	global_store_dwordx2 v[132:133], v[128:129], off offset:1536
	s_and_saveexec_b64 s[8:9], s[2:3]
	s_cbranch_execz .LBB0_242
	v_add_f32_e32 v64, v64, v66
	s_lshl_b64 s[6:7], s[6:7], 6
	v_cndmask_b32_e64 v64, 0, v64, s[4:5]
	v_lshl_add_u64 v[128:129], v[124:125], 0, s[6:7]
	v_mov_b32_e32 v66, v65
	v_mov_b32_e32 v67, v65
	global_store_dwordx4 v[128:129], v[64:67], off
	s_branch .LBB0_242

.LBB0_1571:
	s_waitcnt vmcnt(4)
	s_ashr_i32 s3, s2, 31
	s_waitcnt vmcnt(3)
	v_and_b32_e32 v79, 0xffff0000, v18
	v_lshlrev_b32_e32 v80, 16, v19
	s_waitcnt vmcnt(2)
	v_lshlrev_b32_e32 v82, 16, v20
	s_nop 1
	v_add_f32_dpp v77, v70, v70 quad_perm:[1,0,3,2] row_mask:0xf bank_mask:0xf
	v_and_b32_e32 v83, 0xffff0000, v20
	v_lshlrev_b32_e32 v84, 16, v21
	s_lshl_b64 s[6:7], s[2:3], 12
	s_waitcnt vmcnt(1)
	v_lshlrev_b32_e32 v86, 16, v22
	s_nop 1
	v_add_f32_dpp v77, v77, v77 quad_perm:[2,3,0,1] row_mask:0xf bank_mask:0xf
	v_lshlrev_b32_e32 v78, 16, v18
	v_and_b32_e32 v87, 0xffff0000, v22
	v_lshlrev_b32_e32 v88, 16, v23
	v_lshl_add_u64 v[92:93], v[44:45], 0, s[6:7]
	s_nop 1
	v_add_f32_dpp v77, v77, v77 row_half_mirror row_mask:0xf bank_mask:0xf
	v_and_b32_e32 v81, 0xffff0000, v19
	s_add_i32 s6, s16, s2
	s_cmpk_gt_i32 s6, 0x7fff
	s_nop 1
	v_add_f32_dpp v77, v77, v77 row_mirror row_mask:0xf bank_mask:0xf
	ds_swizzle_b32 v89, v77 offset:swizzle(SWAP,16)
	v_and_b32_e32 v85, 0xffff0000, v21
	s_waitcnt lgkmcnt(0)
	v_add_f32_e32 v77, v77, v89
	v_mov_b32_e32 v89, v77
	s_nop 1
	v_permlane32_swap_b32_e32 v77, v89
	v_add_f32_e32 v77, v77, v89
	v_fmamk_f32 v77, v77, 0x39800000, v73
	v_rsq_f32_e32 v90, v77
	v_and_b32_e32 v89, 0xffff0000, v23
	v_pk_mul_f32 v[78:79], v[90:91], v[78:79] op_sel_hi:[0,1]
	v_pk_mul_f32 v[80:81], v[90:91], v[80:81] op_sel_hi:[0,1]
	v_pk_mul_f32 v[82:83], v[90:91], v[82:83] op_sel_hi:[0,1]
	v_pk_mul_f32 v[84:85], v[90:91], v[84:85] op_sel_hi:[0,1]
	v_pk_mul_f32 v[80:81], v[2:3], v[80:81]
	v_pk_mul_f32 v[78:79], v[0:1], v[78:79]
	v_pk_mul_f32 v[84:85], v[6:7], v[84:85]
	v_pk_mul_f32 v[82:83], v[4:5], v[82:83]
	global_store_dwordx4 v[92:93], v[78:81], off
	global_store_dwordx4 v[92:93], v[82:85], off offset:1024
	s_nop 0
	v_pk_mul_f32 v[78:79], v[90:91], v[86:87] op_sel_hi:[0,1]
	v_pk_mul_f32 v[80:81], v[90:91], v[88:89] op_sel_hi:[0,1]
	v_pk_mul_f32 v[80:81], v[10:11], v[80:81]
	v_pk_mul_f32 v[78:79], v[8:9], v[78:79]
	global_store_dwordx4 v[92:93], v[78:81], off offset:2048
	s_waitcnt vmcnt(3)
	s_nop 0
	v_lshlrev_b32_e32 v78, 16, v24
	v_and_b32_e32 v79, 0xffff0000, v24
	v_lshlrev_b32_e32 v80, 16, v25
	v_and_b32_e32 v81, 0xffff0000, v25
	v_pk_mul_f32 v[78:79], v[90:91], v[78:79] op_sel_hi:[0,1]
	v_pk_mul_f32 v[80:81], v[90:91], v[80:81] op_sel_hi:[0,1]
	v_pk_mul_f32 v[80:81], v[14:15], v[80:81]
	v_pk_mul_f32 v[78:79], v[12:13], v[78:79]
	global_store_dwordx4 v[92:93], v[78:81], off offset:3072
	s_cbranch_scc1 .LBB0_1574
	s_ashr_i32 s7, s6, 31
	v_and_b32_e32 v79, 0xffff0000, v26
	v_lshlrev_b32_e32 v80, 16, v27
	v_lshlrev_b32_e32 v82, 16, v28
	s_nop 1
	v_add_f32_dpp v77, v71, v71 quad_perm:[1,0,3,2] row_mask:0xf bank_mask:0xf
	v_and_b32_e32 v83, 0xffff0000, v28
	v_lshlrev_b32_e32 v84, 16, v29
	s_lshl_b64 s[6:7], s[6:7], 12
	v_lshlrev_b32_e32 v86, 16, v30
	s_nop 1
	v_add_f32_dpp v77, v77, v77 quad_perm:[2,3,0,1] row_mask:0xf bank_mask:0xf
	v_lshlrev_b32_e32 v78, 16, v26
	v_and_b32_e32 v87, 0xffff0000, v30
	v_lshlrev_b32_e32 v88, 16, v31
	v_lshl_add_u64 v[92:93], v[44:45], 0, s[6:7]
	s_nop 1
	v_add_f32_dpp v77, v77, v77 row_half_mirror row_mask:0xf bank_mask:0xf
	v_and_b32_e32 v81, 0xffff0000, v27
	s_nop 1
	v_add_f32_dpp v77, v77, v77 row_mirror row_mask:0xf bank_mask:0xf
	ds_swizzle_b32 v89, v77 offset:swizzle(SWAP,16)
	v_and_b32_e32 v85, 0xffff0000, v29
	s_waitcnt lgkmcnt(0)
	v_add_f32_e32 v77, v77, v89
	v_mov_b32_e32 v89, v77
	s_nop 1
	v_permlane32_swap_b32_e32 v77, v89
	v_add_f32_e32 v77, v77, v89
	v_fmamk_f32 v77, v77, 0x39800000, v73
	v_rsq_f32_e32 v90, v77
	v_and_b32_e32 v89, 0xffff0000, v31
	v_pk_mul_f32 v[78:79], v[90:91], v[78:79] op_sel_hi:[0,1]
	v_pk_mul_f32 v[80:81], v[90:91], v[80:81] op_sel_hi:[0,1]
	v_pk_mul_f32 v[82:83], v[90:91], v[82:83] op_sel_hi:[0,1]
	v_pk_mul_f32 v[84:85], v[90:91], v[84:85] op_sel_hi:[0,1]
	v_pk_mul_f32 v[80:81], v[2:3], v[80:81]
	v_pk_mul_f32 v[78:79], v[0:1], v[78:79]
	v_pk_mul_f32 v[84:85], v[6:7], v[84:85]
	v_pk_mul_f32 v[82:83], v[4:5], v[82:83]
	global_store_dwordx4 v[92:93], v[78:81], off
	global_store_dwordx4 v[92:93], v[82:85], off offset:1024
	s_nop 0
	v_pk_mul_f32 v[78:79], v[90:91], v[86:87] op_sel_hi:[0,1]
	v_pk_mul_f32 v[80:81], v[90:91], v[88:89] op_sel_hi:[0,1]
	v_pk_mul_f32 v[80:81], v[10:11], v[80:81]
	v_pk_mul_f32 v[78:79], v[8:9], v[78:79]
	global_store_dwordx4 v[92:93], v[78:81], off offset:2048
	s_nop 1
	v_lshlrev_b32_e32 v78, 16, v32
	v_and_b32_e32 v79, 0xffff0000, v32
	v_lshlrev_b32_e32 v80, 16, v33
	v_and_b32_e32 v81, 0xffff0000, v33
	v_pk_mul_f32 v[78:79], v[90:91], v[78:79] op_sel_hi:[0,1]
	v_pk_mul_f32 v[80:81], v[90:91], v[80:81] op_sel_hi:[0,1]
	v_pk_mul_f32 v[80:81], v[14:15], v[80:81]
	v_pk_mul_f32 v[78:79], v[12:13], v[78:79]
	global_store_dwordx4 v[92:93], v[78:81], off offset:3072
	s_add_i32 s6, s9, s2
	s_cmpk_gt_i32 s6, 0x7fff
	s_cbranch_scc0 .LBB0_1575

.LBB0_1575:
	s_ashr_i32 s7, s6, 31
	v_and_b32_e32 v79, 0xffff0000, v34
	v_lshlrev_b32_e32 v80, 16, v35
	v_lshlrev_b32_e32 v82, 16, v36
	s_nop 1
	v_add_f32_dpp v77, v72, v72 quad_perm:[1,0,3,2] row_mask:0xf bank_mask:0xf
	v_and_b32_e32 v83, 0xffff0000, v36
	v_lshlrev_b32_e32 v84, 16, v37
	s_lshl_b64 s[6:7], s[6:7], 12
	v_lshlrev_b32_e32 v86, 16, v38
	s_nop 1
	v_add_f32_dpp v77, v77, v77 quad_perm:[2,3,0,1] row_mask:0xf bank_mask:0xf
	v_lshlrev_b32_e32 v78, 16, v34
	v_and_b32_e32 v87, 0xffff0000, v38
	v_lshlrev_b32_e32 v88, 16, v39
	v_lshl_add_u64 v[92:93], v[44:45], 0, s[6:7]
	s_nop 1
	v_add_f32_dpp v77, v77, v77 row_half_mirror row_mask:0xf bank_mask:0xf
	v_and_b32_e32 v81, 0xffff0000, v35
	s_nop 1
	v_add_f32_dpp v77, v77, v77 row_mirror row_mask:0xf bank_mask:0xf
	ds_swizzle_b32 v89, v77 offset:swizzle(SWAP,16)
	v_and_b32_e32 v85, 0xffff0000, v37
	s_waitcnt lgkmcnt(0)
	v_add_f32_e32 v77, v77, v89
	v_mov_b32_e32 v89, v77
	s_nop 1
	v_permlane32_swap_b32_e32 v77, v89
	v_add_f32_e32 v77, v77, v89
	v_fmamk_f32 v77, v77, 0x39800000, v73
	v_rsq_f32_e32 v90, v77
	v_and_b32_e32 v89, 0xffff0000, v39
	v_pk_mul_f32 v[78:79], v[90:91], v[78:79] op_sel_hi:[0,1]
	v_pk_mul_f32 v[80:81], v[90:91], v[80:81] op_sel_hi:[0,1]
	v_pk_mul_f32 v[82:83], v[90:91], v[82:83] op_sel_hi:[0,1]
	v_pk_mul_f32 v[84:85], v[90:91], v[84:85] op_sel_hi:[0,1]
	v_pk_mul_f32 v[80:81], v[2:3], v[80:81]
	v_pk_mul_f32 v[78:79], v[0:1], v[78:79]
	v_pk_mul_f32 v[84:85], v[6:7], v[84:85]
	v_pk_mul_f32 v[82:83], v[4:5], v[82:83]
	global_store_dwordx4 v[92:93], v[78:81], off
	global_store_dwordx4 v[92:93], v[82:85], off offset:1024
	s_nop 0
	v_pk_mul_f32 v[78:79], v[90:91], v[86:87] op_sel_hi:[0,1]
	v_pk_mul_f32 v[80:81], v[90:91], v[88:89] op_sel_hi:[0,1]
	v_pk_mul_f32 v[80:81], v[10:11], v[80:81]
	v_pk_mul_f32 v[78:79], v[8:9], v[78:79]
	global_store_dwordx4 v[92:93], v[78:81], off offset:2048
	s_nop 1
	v_lshlrev_b32_e32 v78, 16, v40
	v_and_b32_e32 v79, 0xffff0000, v40
	v_lshlrev_b32_e32 v80, 16, v41
	v_and_b32_e32 v81, 0xffff0000, v41
	v_pk_mul_f32 v[78:79], v[90:91], v[78:79] op_sel_hi:[0,1]
	v_pk_mul_f32 v[80:81], v[90:91], v[80:81] op_sel_hi:[0,1]
	v_pk_mul_f32 v[80:81], v[14:15], v[80:81]
	v_pk_mul_f32 v[78:79], v[12:13], v[78:79]
	global_store_dwordx4 v[92:93], v[78:81], off offset:3072
	s_andn2_b64 vcc, exec, s[4:5]
	s_add_i32 s4, s8, s2
	s_cbranch_vccnz .LBB0_1565

.LBB0_1581:
	s_ashr_i32 s1, s0, 31
	v_and_b32_e32 v79, 0xffff0000, v62
	v_lshlrev_b32_e32 v80, 16, v63
	v_lshlrev_b32_e32 v82, 16, v64
	s_nop 1
	v_add_f32_dpp v77, v76, v76 quad_perm:[1,0,3,2] row_mask:0xf bank_mask:0xf
	v_and_b32_e32 v83, 0xffff0000, v64
	v_lshlrev_b32_e32 v84, 16, v65
	s_lshl_b64 s[0:1], s[0:1], 12
	v_lshlrev_b32_e32 v86, 16, v66
	s_nop 1
	v_add_f32_dpp v77, v77, v77 quad_perm:[2,3,0,1] row_mask:0xf bank_mask:0xf
	v_lshlrev_b32_e32 v78, 16, v62
	v_and_b32_e32 v87, 0xffff0000, v66
	v_lshlrev_b32_e32 v88, 16, v67
	v_lshl_add_u64 v[92:93], v[44:45], 0, s[0:1]
	s_nop 1
	v_add_f32_dpp v77, v77, v77 row_half_mirror row_mask:0xf bank_mask:0xf
	v_and_b32_e32 v81, 0xffff0000, v63
	v_readlane_b32 s0, v254, 7
	s_add_i32 s0, s0, s2
	s_cmpk_gt_i32 s0, 0x7fff
	s_nop 1
	v_add_f32_dpp v77, v77, v77 row_mirror row_mask:0xf bank_mask:0xf
	ds_swizzle_b32 v89, v77 offset:swizzle(SWAP,16)
	v_and_b32_e32 v85, 0xffff0000, v65
	s_waitcnt lgkmcnt(0)
	v_add_f32_e32 v77, v77, v89
	v_mov_b32_e32 v89, v77
	s_nop 1
	v_permlane32_swap_b32_e32 v77, v89
	v_add_f32_e32 v77, v77, v89
	v_fmamk_f32 v77, v77, 0x39800000, v73
	v_rsq_f32_e32 v90, v77
	v_and_b32_e32 v89, 0xffff0000, v67
	v_pk_mul_f32 v[78:79], v[90:91], v[78:79] op_sel_hi:[0,1]
	v_pk_mul_f32 v[80:81], v[90:91], v[80:81] op_sel_hi:[0,1]
	v_pk_mul_f32 v[82:83], v[90:91], v[82:83] op_sel_hi:[0,1]
	v_pk_mul_f32 v[84:85], v[90:91], v[84:85] op_sel_hi:[0,1]
	v_pk_mul_f32 v[80:81], v[2:3], v[80:81]
	v_pk_mul_f32 v[78:79], v[0:1], v[78:79]
	v_pk_mul_f32 v[84:85], v[6:7], v[84:85]
	v_pk_mul_f32 v[82:83], v[4:5], v[82:83]
	global_store_dwordx4 v[92:93], v[78:81], off
	global_store_dwordx4 v[92:93], v[82:85], off offset:1024
	s_nop 0
	v_pk_mul_f32 v[78:79], v[90:91], v[86:87] op_sel_hi:[0,1]
	v_pk_mul_f32 v[80:81], v[90:91], v[88:89] op_sel_hi:[0,1]
	v_pk_mul_f32 v[80:81], v[10:11], v[80:81]
	v_pk_mul_f32 v[78:79], v[8:9], v[78:79]
	global_store_dwordx4 v[92:93], v[78:81], off offset:2048
	s_nop 1
	v_lshlrev_b32_e32 v78, 16, v68
	v_and_b32_e32 v79, 0xffff0000, v68
	v_lshlrev_b32_e32 v80, 16, v69
	v_and_b32_e32 v81, 0xffff0000, v69
	v_pk_mul_f32 v[78:79], v[90:91], v[78:79] op_sel_hi:[0,1]
	v_pk_mul_f32 v[80:81], v[90:91], v[80:81] op_sel_hi:[0,1]
	v_pk_mul_f32 v[80:81], v[14:15], v[80:81]
	v_pk_mul_f32 v[78:79], v[12:13], v[78:79]
	global_store_dwordx4 v[92:93], v[78:81], off offset:3072
	s_cbranch_scc1 .LBB0_1583
	s_ashr_i32 s1, s0, 31
	v_and_b32_e32 v79, 0xffff0000, v60
	v_lshlrev_b32_e32 v80, 16, v61
	v_lshlrev_b32_e32 v82, 16, v58
	s_nop 1
	v_add_f32_dpp v77, v75, v75 quad_perm:[1,0,3,2] row_mask:0xf bank_mask:0xf
	v_and_b32_e32 v83, 0xffff0000, v58
	v_lshlrev_b32_e32 v84, 16, v59
	s_lshl_b64 s[0:1], s[0:1], 12
	v_lshlrev_b32_e32 v86, 16, v56
	s_nop 1
	v_add_f32_dpp v77, v77, v77 quad_perm:[2,3,0,1] row_mask:0xf bank_mask:0xf
	v_lshlrev_b32_e32 v78, 16, v60
	v_and_b32_e32 v87, 0xffff0000, v56
	v_lshlrev_b32_e32 v88, 16, v57
	v_lshl_add_u64 v[92:93], v[44:45], 0, s[0:1]
	s_nop 1
	v_add_f32_dpp v77, v77, v77 row_half_mirror row_mask:0xf bank_mask:0xf
	v_and_b32_e32 v81, 0xffff0000, v61
	s_nop 1
	v_add_f32_dpp v77, v77, v77 row_mirror row_mask:0xf bank_mask:0xf
	ds_swizzle_b32 v89, v77 offset:swizzle(SWAP,16)
	v_and_b32_e32 v85, 0xffff0000, v59
	s_waitcnt lgkmcnt(0)
	v_add_f32_e32 v77, v77, v89
	v_mov_b32_e32 v89, v77
	s_nop 1
	v_permlane32_swap_b32_e32 v77, v89
	v_add_f32_e32 v77, v77, v89
	v_fmamk_f32 v77, v77, 0x39800000, v73
	v_rsq_f32_e32 v90, v77
	v_and_b32_e32 v89, 0xffff0000, v57
	v_pk_mul_f32 v[78:79], v[90:91], v[78:79] op_sel_hi:[0,1]
	v_pk_mul_f32 v[80:81], v[90:91], v[80:81] op_sel_hi:[0,1]
	v_pk_mul_f32 v[82:83], v[90:91], v[82:83] op_sel_hi:[0,1]
	v_pk_mul_f32 v[84:85], v[90:91], v[84:85] op_sel_hi:[0,1]
	v_pk_mul_f32 v[80:81], v[2:3], v[80:81]
	v_pk_mul_f32 v[78:79], v[0:1], v[78:79]
	v_pk_mul_f32 v[84:85], v[6:7], v[84:85]
	v_pk_mul_f32 v[82:83], v[4:5], v[82:83]
	global_store_dwordx4 v[92:93], v[78:81], off
	global_store_dwordx4 v[92:93], v[82:85], off offset:1024
	s_nop 0
	v_pk_mul_f32 v[78:79], v[90:91], v[86:87] op_sel_hi:[0,1]
	v_pk_mul_f32 v[80:81], v[90:91], v[88:89] op_sel_hi:[0,1]
	v_pk_mul_f32 v[80:81], v[10:11], v[80:81]
	v_pk_mul_f32 v[78:79], v[8:9], v[78:79]
	global_store_dwordx4 v[92:93], v[78:81], off offset:2048
	s_nop 1
	v_lshlrev_b32_e32 v78, 16, v54
	v_and_b32_e32 v79, 0xffff0000, v54
	v_lshlrev_b32_e32 v80, 16, v55
	v_and_b32_e32 v81, 0xffff0000, v55
	v_pk_mul_f32 v[78:79], v[90:91], v[78:79] op_sel_hi:[0,1]
	v_pk_mul_f32 v[80:81], v[90:91], v[80:81] op_sel_hi:[0,1]
	v_pk_mul_f32 v[80:81], v[14:15], v[80:81]
	v_pk_mul_f32 v[78:79], v[12:13], v[78:79]
	global_store_dwordx4 v[92:93], v[78:81], off offset:3072
.LBB0_1583:
	s_add_i32 s0, s11, s2
	s_cmpk_gt_i32 s0, 0x7fff
	s_cbranch_scc1 .LBB0_1565
	s_ashr_i32 s1, s0, 31
	v_and_b32_e32 v79, 0xffff0000, v52
	v_lshlrev_b32_e32 v80, 16, v53
	v_lshlrev_b32_e32 v82, 16, v50
	s_nop 1
	v_add_f32_dpp v77, v74, v74 quad_perm:[1,0,3,2] row_mask:0xf bank_mask:0xf
	v_and_b32_e32 v83, 0xffff0000, v50
	v_lshlrev_b32_e32 v84, 16, v51
	s_lshl_b64 s[0:1], s[0:1], 12
	v_lshlrev_b32_e32 v86, 16, v48
	s_nop 1
	v_add_f32_dpp v77, v77, v77 quad_perm:[2,3,0,1] row_mask:0xf bank_mask:0xf
	v_lshlrev_b32_e32 v78, 16, v52
	v_and_b32_e32 v87, 0xffff0000, v48
	v_lshlrev_b32_e32 v88, 16, v49
	v_lshl_add_u64 v[92:93], v[44:45], 0, s[0:1]
	s_nop 1
	v_add_f32_dpp v77, v77, v77 row_half_mirror row_mask:0xf bank_mask:0xf
	v_and_b32_e32 v81, 0xffff0000, v53
	s_nop 1
	v_add_f32_dpp v77, v77, v77 row_mirror row_mask:0xf bank_mask:0xf
	ds_swizzle_b32 v89, v77 offset:swizzle(SWAP,16)
	v_and_b32_e32 v85, 0xffff0000, v51
	s_waitcnt lgkmcnt(0)
	v_add_f32_e32 v77, v77, v89
	v_mov_b32_e32 v89, v77
	s_nop 1
	v_permlane32_swap_b32_e32 v77, v89
	v_add_f32_e32 v77, v77, v89
	v_fmamk_f32 v77, v77, 0x39800000, v73
	v_rsq_f32_e32 v90, v77
	v_and_b32_e32 v89, 0xffff0000, v49
	v_pk_mul_f32 v[78:79], v[90:91], v[78:79] op_sel_hi:[0,1]
	v_pk_mul_f32 v[80:81], v[90:91], v[80:81] op_sel_hi:[0,1]
	v_pk_mul_f32 v[82:83], v[90:91], v[82:83] op_sel_hi:[0,1]
	v_pk_mul_f32 v[84:85], v[90:91], v[84:85] op_sel_hi:[0,1]
	v_pk_mul_f32 v[80:81], v[2:3], v[80:81]
	v_pk_mul_f32 v[78:79], v[0:1], v[78:79]
	v_pk_mul_f32 v[84:85], v[6:7], v[84:85]
	v_pk_mul_f32 v[82:83], v[4:5], v[82:83]
	global_store_dwordx4 v[92:93], v[78:81], off
	global_store_dwordx4 v[92:93], v[82:85], off offset:1024
	s_nop 0
	v_pk_mul_f32 v[78:79], v[90:91], v[86:87] op_sel_hi:[0,1]
	v_pk_mul_f32 v[80:81], v[90:91], v[88:89] op_sel_hi:[0,1]
	v_pk_mul_f32 v[80:81], v[10:11], v[80:81]
	v_pk_mul_f32 v[78:79], v[8:9], v[78:79]
	global_store_dwordx4 v[92:93], v[78:81], off offset:2048
	s_nop 1
	v_lshlrev_b32_e32 v78, 16, v46
	v_and_b32_e32 v79, 0xffff0000, v46
	v_lshlrev_b32_e32 v80, 16, v47
	v_and_b32_e32 v81, 0xffff0000, v47
	v_pk_mul_f32 v[78:79], v[90:91], v[78:79] op_sel_hi:[0,1]
	v_pk_mul_f32 v[80:81], v[90:91], v[80:81] op_sel_hi:[0,1]
	v_pk_mul_f32 v[80:81], v[14:15], v[80:81]
	v_pk_mul_f32 v[78:79], v[12:13], v[78:79]
	global_store_dwordx4 v[92:93], v[78:81], off offset:3072
	s_branch .LBB0_1565
